# attention loops: the four NaN-quieting self-max ops per key tile on the serial row-max chain removed (v_max_f32 already drops NaNs)
# speedup vs baseline: 1.0065x; 1.0064x over previous
.LBB0_606:
	v_add_u32_e32 v166, s56, v195
	ds_read_b64_tr_b16 v[162:163], v166 offset:24576
	ds_read_b64_tr_b16 v[164:165], v166 offset:25088
	s_waitcnt lgkmcnt(9)
	v_mfma_f32_32x32x16_bf16 v[82:97], v[158:161], v[126:129], v[82:97]
	v_add_f32_e32 v102, v50, v51
	v_add_f32_e32 v102, v52, v102
	v_add_f32_e32 v102, v53, v102
	v_add_f32_e32 v102, v54, v102
	v_add_f32_e32 v102, v55, v102
	v_cvt_pk_bf16_f32 v122, v50, v51
	v_cvt_pk_bf16_f32 v123, v52, v53
	ds_read_b64_tr_b16 v[50:51], v166 offset:28672
	ds_read_b64_tr_b16 v[52:53], v166 offset:29184
	s_waitcnt lgkmcnt(10)
	v_mfma_f32_32x32x16_bf16 v[66:81], v[154:157], v[126:129], v[66:81]
	v_add_f32_e32 v102, v56, v102
	v_add_f32_e32 v102, v57, v102
	v_add_f32_e32 v102, v58, v102
	v_add_f32_e32 v102, v59, v102
	v_cvt_pk_bf16_f32 v124, v54, v55
	v_cvt_pk_bf16_f32 v125, v56, v57
	ds_read_b64_tr_b16 v[54:55], v166 offset:25600
	ds_read_b64_tr_b16 v[56:57], v166 offset:26112
	s_waitcnt lgkmcnt(11)
	v_mfma_f32_32x32x16_bf16 v[82:97], v[150:153], v[118:121], v[82:97]
	v_add_f32_e32 v102, v60, v102
	v_add_f32_e32 v102, v61, v102
	v_add_f32_e32 v102, v62, v102
	v_add_f32_e32 v102, v63, v102
	v_cvt_pk_bf16_f32 v114, v58, v59
	v_cvt_pk_bf16_f32 v115, v60, v61
	ds_read_b64_tr_b16 v[58:59], v166 offset:29696
	ds_read_b64_tr_b16 v[60:61], v166 offset:30208
	s_waitcnt lgkmcnt(12)
	v_mfma_f32_32x32x16_bf16 v[66:81], v[146:149], v[118:121], v[66:81]
	v_add_f32_e32 v102, v64, v102
	v_add_f32_e32 v102, v65, v102
	v_add_f32_e32 v102, v34, v102
	v_add_f32_e32 v102, v35, v102
	v_cvt_pk_bf16_f32 v116, v62, v63
	v_cvt_pk_bf16_f32 v117, v64, v65
	ds_read_b64_tr_b16 v[62:63], v166 offset:26624
	ds_read_b64_tr_b16 v[64:65], v166 offset:27136
	s_waitcnt lgkmcnt(13)
	v_mfma_f32_32x32x16_bf16 v[82:97], v[142:145], v[106:109], v[82:97]
	v_add_f32_e32 v102, v36, v102
	v_add_f32_e32 v102, v37, v102
	v_add_f32_e32 v102, v38, v102
	v_add_f32_e32 v102, v39, v102
	v_cvt_pk_bf16_f32 v110, v34, v35
	v_cvt_pk_bf16_f32 v111, v36, v37
	ds_read_b64_tr_b16 v[34:35], v166 offset:30720
	ds_read_b64_tr_b16 v[36:37], v166 offset:31232
	s_waitcnt lgkmcnt(14)
	v_mfma_f32_32x32x16_bf16 v[66:81], v[138:141], v[106:109], v[66:81]
	v_add_f32_e32 v102, v40, v102
	v_add_f32_e32 v102, v41, v102
	v_add_f32_e32 v102, v42, v102
	v_add_f32_e32 v102, v43, v102
	v_cvt_pk_bf16_f32 v112, v38, v39
	v_cvt_pk_bf16_f32 v113, v40, v41
	ds_read_b64_tr_b16 v[38:39], v166 offset:27648
	ds_read_b64_tr_b16 v[40:41], v166 offset:28160
	s_waitcnt lgkmcnt(14)
	v_mfma_f32_32x32x16_bf16 v[82:97], v[134:137], v[98:101], v[82:97]
	v_add_f32_e32 v102, v44, v102
	v_add_f32_e32 v102, v45, v102
	v_add_f32_e32 v102, v46, v102
	v_add_f32_e32 v134, v47, v102
	v_cvt_pk_bf16_f32 v102, v42, v43
	v_cvt_pk_bf16_f32 v103, v44, v45
	ds_read_b64_tr_b16 v[42:43], v166 offset:31744
	ds_read_b64_tr_b16 v[44:45], v166 offset:32256
	v_mfma_f32_32x32x16_bf16 v[66:81], v[130:133], v[98:101], v[66:81]
	v_add_f32_e32 v104, v48, v134
	v_add_f32_e32 v104, v49, v104
	v_add_f32_e32 v130, 0, v104
	v_cvt_pk_bf16_f32 v104, v46, v47
	v_cvt_pk_bf16_f32 v105, v48, v49
	s_add_i32 s30, s31, s33
	s_sub_i32 s0, s30, 64
	v_mad_i64_i32 v[46:47], s[0:1], s0, v217, v[174:175]
	s_add_i32 s0, s35, s21
	s_cmp_lt_u32 s34, 3
	s_mov_b32 s1, m0
	s_mov_b32 m0, s0
	s_nop 0
	global_load_lds_dwordx4 v[46:47], off
	s_mov_b32 m0, s1
	s_cselect_b32 s0, s7, s9
	s_add_i32 s0, s0, s33
	v_mad_i64_i32 v[46:47], s[0:1], s0, v217, v[176:177]
	s_add_i32 s0, s6, s22
	s_mov_b32 s1, m0
	s_mov_b32 m0, s0
	s_nop 0
	global_load_lds_dwordx4 v[46:47], off
	s_mov_b32 m0, s1
	v_max_f32_e32 v46, v82, v83
	v_max3_f32 v47, v84, v85, v67
	v_max3_f32 v46, v46, v66, v68
	v_max3_f32 v46, v46, v69, v86
	v_max3_f32 v47, v47, v88, v89
	v_max3_f32 v46, v46, v87, v70
	v_max3_f32 v47, v47, v72, v73
	v_max3_f32 v46, v46, v71, v90
	v_max3_f32 v47, v47, v92, v93
	v_max3_f32 v46, v46, v91, v74
	v_max3_f32 v47, v47, v76, v77
	v_max3_f32 v46, v46, v75, v94
	v_max3_f32 v47, v47, v96, v97
	v_max3_f32 v46, v46, v95, v78
	v_max3_f32 v47, v47, v80, v81
	v_max3_f32 v46, v46, v79, v47
	v_mov_b32_e32 v47, v46
	s_nop 1
	v_permlane32_swap_b32_e32 v46, v47
	v_max_f32_e32 v46, v46, v47
	v_cmp_lt_f32_e32 vcc, s51, v46
	s_cmp_lg_u64 vcc, 0
	v_add_f32_e32 v166, v200, v130
	s_cselect_b64 s[0:1], -1, 0
	s_cbranch_vccnz .LBB0_622

.LBB0_617:
	s_add_i32 s0, s6, 0x2000
	s_cmpk_lg_i32 s6, 0x4000
	s_cselect_b32 s29, s0, 0
	v_add_u32_e32 v167, s35, v195
	ds_read_b64_tr_b16 v[162:163], v167 offset:24576
	ds_read_b64_tr_b16 v[164:165], v167 offset:25088
	s_waitcnt lgkmcnt(9)
	v_mfma_f32_32x32x16_bf16 v[50:65], v[158:161], v[126:129], v[50:65]
	v_add_f32_e32 v102, v82, v83
	v_add_f32_e32 v102, v84, v102
	v_add_f32_e32 v102, v85, v102
	v_add_f32_e32 v102, v86, v102
	v_add_f32_e32 v102, v87, v102
	v_cvt_pk_bf16_f32 v122, v82, v83
	v_cvt_pk_bf16_f32 v123, v84, v85
	ds_read_b64_tr_b16 v[82:83], v167 offset:28672
	ds_read_b64_tr_b16 v[84:85], v167 offset:29184
	s_waitcnt lgkmcnt(10)
	v_mfma_f32_32x32x16_bf16 v[34:49], v[154:157], v[126:129], v[34:49]
	v_add_f32_e32 v102, v88, v102
	v_add_f32_e32 v102, v89, v102
	v_add_f32_e32 v102, v90, v102
	v_add_f32_e32 v102, v91, v102
	v_cvt_pk_bf16_f32 v124, v86, v87
	v_cvt_pk_bf16_f32 v125, v88, v89
	ds_read_b64_tr_b16 v[86:87], v167 offset:25600
	ds_read_b64_tr_b16 v[88:89], v167 offset:26112
	s_waitcnt lgkmcnt(11)
	v_mfma_f32_32x32x16_bf16 v[50:65], v[150:153], v[118:121], v[50:65]
	v_add_f32_e32 v102, v92, v102
	v_add_f32_e32 v102, v93, v102
	v_add_f32_e32 v102, v94, v102
	v_add_f32_e32 v102, v95, v102
	v_cvt_pk_bf16_f32 v114, v90, v91
	v_cvt_pk_bf16_f32 v115, v92, v93
	ds_read_b64_tr_b16 v[90:91], v167 offset:29696
	ds_read_b64_tr_b16 v[92:93], v167 offset:30208
	s_waitcnt lgkmcnt(12)
	v_mfma_f32_32x32x16_bf16 v[34:49], v[146:149], v[118:121], v[34:49]
	v_add_f32_e32 v102, v96, v102
	v_add_f32_e32 v102, v97, v102
	v_add_f32_e32 v102, v66, v102
	v_add_f32_e32 v102, v67, v102
	v_cvt_pk_bf16_f32 v116, v94, v95
	v_cvt_pk_bf16_f32 v117, v96, v97
	ds_read_b64_tr_b16 v[94:95], v167 offset:26624
	ds_read_b64_tr_b16 v[96:97], v167 offset:27136
	s_waitcnt lgkmcnt(13)
	v_mfma_f32_32x32x16_bf16 v[50:65], v[142:145], v[106:109], v[50:65]
	v_add_f32_e32 v102, v68, v102
	v_add_f32_e32 v102, v69, v102
	v_add_f32_e32 v102, v70, v102
	v_add_f32_e32 v102, v71, v102
	v_cvt_pk_bf16_f32 v110, v66, v67
	v_cvt_pk_bf16_f32 v111, v68, v69
	ds_read_b64_tr_b16 v[66:67], v167 offset:30720
	ds_read_b64_tr_b16 v[68:69], v167 offset:31232
	s_waitcnt lgkmcnt(14)
	v_mfma_f32_32x32x16_bf16 v[34:49], v[138:141], v[106:109], v[34:49]
	v_add_f32_e32 v102, v72, v102
	v_add_f32_e32 v102, v73, v102
	v_add_f32_e32 v102, v74, v102
	v_add_f32_e32 v102, v75, v102
	v_cvt_pk_bf16_f32 v112, v70, v71
	v_cvt_pk_bf16_f32 v113, v72, v73
	ds_read_b64_tr_b16 v[70:71], v167 offset:27648
	ds_read_b64_tr_b16 v[72:73], v167 offset:28160
	s_waitcnt lgkmcnt(14)
	v_mfma_f32_32x32x16_bf16 v[50:65], v[134:137], v[98:101], v[50:65]
	v_add_f32_e32 v102, v76, v102
	v_add_f32_e32 v102, v77, v102
	v_add_f32_e32 v102, v78, v102
	v_add_f32_e32 v134, v79, v102
	v_cvt_pk_bf16_f32 v102, v74, v75
	v_cvt_pk_bf16_f32 v103, v76, v77
	ds_read_b64_tr_b16 v[74:75], v167 offset:31744
	ds_read_b64_tr_b16 v[76:77], v167 offset:32256
	v_mfma_f32_32x32x16_bf16 v[34:49], v[130:133], v[98:101], v[34:49]
	v_add_f32_e32 v104, v80, v134
	v_add_f32_e32 v104, v81, v104
	v_add_f32_e32 v130, 0, v104
	v_cvt_pk_bf16_f32 v104, v78, v79
	v_cvt_pk_bf16_f32 v105, v80, v81
	v_mad_i64_i32 v[78:79], s[0:1], s30, v217, v[174:175]
	s_add_i32 s0, s6, s21
	s_cmp_lt_u32 s34, 2
	s_mov_b32 s1, m0
	s_mov_b32 m0, s0
	s_nop 0
	global_load_lds_dwordx4 v[78:79], off
	s_mov_b32 m0, s1
	s_cselect_b32 s0, s8, s10
	s_add_i32 s0, s0, s33
	v_mad_i64_i32 v[78:79], s[0:1], s0, v217, v[176:177]
	s_add_i32 s0, s29, s22
	s_mov_b32 s1, m0
	s_mov_b32 m0, s0
	s_nop 0
	global_load_lds_dwordx4 v[78:79], off
	s_mov_b32 m0, s1
	v_max_f32_e32 v78, v50, v51
	v_max3_f32 v79, v52, v53, v35
	v_max3_f32 v78, v78, v34, v36
	v_max3_f32 v78, v78, v37, v54
	v_max3_f32 v79, v79, v56, v57
	v_max3_f32 v78, v78, v55, v38
	v_max3_f32 v79, v79, v40, v41
	v_max3_f32 v78, v78, v39, v58
	v_max3_f32 v79, v79, v60, v61
	v_max3_f32 v78, v78, v59, v42
	v_max3_f32 v79, v79, v44, v45
	v_max3_f32 v78, v78, v43, v62
	v_max3_f32 v79, v79, v64, v65
	v_max3_f32 v78, v78, v63, v46
	v_max3_f32 v79, v79, v48, v49
	v_max3_f32 v78, v78, v47, v79
	v_mov_b32_e32 v79, v78
	s_nop 1
	v_permlane32_swap_b32_e32 v78, v79
	v_max_f32_e32 v78, v78, v79
	v_cmp_lt_f32_e32 vcc, s51, v78
	s_cmp_lg_u64 vcc, 0
	v_add_f32_e32 v200, v166, v130
	s_cselect_b64 s[0:1], -1, 0
	s_cbranch_vccnz .LBB0_625

.LBB0_637:
	s_add_i32 s0, s28, 0xffffff80
	v_mad_i64_i32 v[46:47], s[0:1], s0, v217, v[176:177]
	s_add_i32 s0, s30, s22
	s_mov_b32 s1, m0
	s_mov_b32 m0, s0
	s_nop 0
	global_load_lds_dwordx4 v[46:47], off
	s_mov_b32 m0, s1
	v_max_f32_e32 v46, v82, v83
	v_max3_f32 v47, v84, v85, v67
	v_max3_f32 v46, v46, v66, v68
	v_max3_f32 v46, v46, v69, v86
	v_max3_f32 v47, v47, v88, v89
	v_max3_f32 v46, v46, v87, v70
	v_max3_f32 v47, v47, v72, v73
	v_max3_f32 v46, v46, v71, v90
	v_max3_f32 v47, v47, v92, v93
	v_max3_f32 v46, v46, v91, v74
	v_max3_f32 v47, v47, v76, v77
	v_max3_f32 v46, v46, v75, v94
	v_max3_f32 v47, v47, v96, v97
	v_max3_f32 v46, v46, v95, v78
	v_max3_f32 v47, v47, v80, v81
	v_max3_f32 v46, v46, v79, v47
	v_mov_b32_e32 v47, v46
	s_nop 1
	v_permlane32_swap_b32_e32 v46, v47
	v_max_f32_e32 v46, v46, v47
	v_cmp_lt_f32_e32 vcc, s51, v46
	s_cmp_lg_u64 vcc, 0
	v_add_f32_e32 v200, v200, v130
	s_cselect_b64 s[0:1], -1, 0
	s_cbranch_vccnz .LBB0_678

.LBB0_655:
	v_add_f32_e32 v200, v200, v74
	v_max_f32_e32 v74, v50, v51
	v_max3_f32 v75, v52, v53, v35
	v_max3_f32 v74, v74, v34, v36
	v_max3_f32 v74, v74, v37, v54
	v_max3_f32 v75, v75, v56, v57
	v_max3_f32 v74, v74, v55, v38
	v_max3_f32 v75, v75, v40, v41
	v_max3_f32 v74, v74, v39, v58
	v_max3_f32 v75, v75, v60, v61
	v_max3_f32 v74, v74, v59, v42
	v_max3_f32 v75, v75, v44, v45
	v_max3_f32 v74, v74, v43, v62
	v_max3_f32 v75, v75, v64, v65
	v_max3_f32 v74, v74, v63, v46
	v_max3_f32 v75, v75, v48, v49
	v_max3_f32 v74, v74, v47, v75
	v_mov_b32_e32 v75, v74
	s_nop 1
	v_permlane32_swap_b32_e32 v74, v75
	v_max_f32_e32 v74, v74, v75
	v_cmp_lt_f32_e32 vcc, s51, v74
	s_cmp_lg_u64 vcc, 0
	s_cselect_b64 s[6:7], -1, 0
	s_cbranch_vccnz .LBB0_681

.LBB0_690:
	v_add_u32_e32 v166, s30, v195
	ds_read_b64_tr_b16 v[162:163], v166 offset:24576
	ds_read_b64_tr_b16 v[164:165], v166 offset:25088
	s_waitcnt lgkmcnt(9)
	v_mfma_f32_32x32x16_bf16 v[82:97], v[158:161], v[126:129], v[82:97]
	v_add_f32_e32 v102, v50, v51
	v_add_f32_e32 v102, v52, v102
	v_add_f32_e32 v102, v53, v102
	v_add_f32_e32 v102, v54, v102
	v_add_f32_e32 v102, v55, v102
	v_cvt_pk_bf16_f32 v122, v50, v51
	v_cvt_pk_bf16_f32 v123, v52, v53
	ds_read_b64_tr_b16 v[50:51], v166 offset:28672
	ds_read_b64_tr_b16 v[52:53], v166 offset:29184
	s_waitcnt lgkmcnt(10)
	v_mfma_f32_32x32x16_bf16 v[66:81], v[154:157], v[126:129], v[66:81]
	v_add_f32_e32 v102, v56, v102
	v_add_f32_e32 v102, v57, v102
	v_add_f32_e32 v102, v58, v102
	v_add_f32_e32 v102, v59, v102
	v_cvt_pk_bf16_f32 v124, v54, v55
	v_cvt_pk_bf16_f32 v125, v56, v57
	ds_read_b64_tr_b16 v[54:55], v166 offset:25600
	ds_read_b64_tr_b16 v[56:57], v166 offset:26112
	s_waitcnt lgkmcnt(11)
	v_mfma_f32_32x32x16_bf16 v[82:97], v[150:153], v[118:121], v[82:97]
	v_add_f32_e32 v102, v60, v102
	v_add_f32_e32 v102, v61, v102
	v_add_f32_e32 v102, v62, v102
	v_add_f32_e32 v102, v63, v102
	v_cvt_pk_bf16_f32 v114, v58, v59
	v_cvt_pk_bf16_f32 v115, v60, v61
	ds_read_b64_tr_b16 v[58:59], v166 offset:29696
	ds_read_b64_tr_b16 v[60:61], v166 offset:30208
	s_waitcnt lgkmcnt(12)
	v_mfma_f32_32x32x16_bf16 v[66:81], v[146:149], v[118:121], v[66:81]
	v_add_f32_e32 v102, v64, v102
	v_add_f32_e32 v102, v65, v102
	v_add_f32_e32 v102, v34, v102
	v_add_f32_e32 v102, v35, v102
	v_cvt_pk_bf16_f32 v116, v62, v63
	v_cvt_pk_bf16_f32 v117, v64, v65
	ds_read_b64_tr_b16 v[62:63], v166 offset:26624
	ds_read_b64_tr_b16 v[64:65], v166 offset:27136
	s_waitcnt lgkmcnt(13)
	v_mfma_f32_32x32x16_bf16 v[82:97], v[142:145], v[106:109], v[82:97]
	v_add_f32_e32 v102, v36, v102
	v_add_f32_e32 v102, v37, v102
	v_add_f32_e32 v102, v38, v102
	v_add_f32_e32 v102, v39, v102
	v_cvt_pk_bf16_f32 v110, v34, v35
	v_cvt_pk_bf16_f32 v111, v36, v37
	ds_read_b64_tr_b16 v[34:35], v166 offset:30720
	ds_read_b64_tr_b16 v[36:37], v166 offset:31232
	s_waitcnt lgkmcnt(14)
	v_mfma_f32_32x32x16_bf16 v[66:81], v[138:141], v[106:109], v[66:81]
	v_add_f32_e32 v102, v40, v102
	v_add_f32_e32 v102, v41, v102
	v_add_f32_e32 v102, v42, v102
	v_add_f32_e32 v102, v43, v102
	v_cvt_pk_bf16_f32 v112, v38, v39
	v_cvt_pk_bf16_f32 v113, v40, v41
	ds_read_b64_tr_b16 v[38:39], v166 offset:27648
	ds_read_b64_tr_b16 v[40:41], v166 offset:28160
	s_waitcnt lgkmcnt(14)
	v_mfma_f32_32x32x16_bf16 v[82:97], v[134:137], v[98:101], v[82:97]
	v_add_f32_e32 v102, v44, v102
	v_add_f32_e32 v102, v45, v102
	v_add_f32_e32 v102, v46, v102
	v_add_f32_e32 v106, v47, v102
	v_cvt_pk_bf16_f32 v102, v42, v43
	v_cvt_pk_bf16_f32 v103, v44, v45
	ds_read_b64_tr_b16 v[42:43], v166 offset:31744
	ds_read_b64_tr_b16 v[44:45], v166 offset:32256
	v_mfma_f32_32x32x16_bf16 v[66:81], v[130:133], v[98:101], v[66:81]
	v_add_f32_e32 v98, v48, v106
	v_add_f32_e32 v98, v49, v98
	v_add_f32_e32 v98, 0, v98
	v_cvt_pk_bf16_f32 v104, v46, v47
	v_cvt_pk_bf16_f32 v105, v48, v49
	v_max_f32_e32 v46, v82, v83
	s_nop 3
	v_max3_f32 v47, v84, v85, v67
	v_max3_f32 v46, v46, v66, v68
	v_max3_f32 v46, v46, v69, v86
	v_max3_f32 v47, v47, v88, v89
	v_max3_f32 v46, v46, v87, v70
	v_max3_f32 v47, v47, v72, v73
	v_max3_f32 v46, v46, v71, v90
	v_max3_f32 v47, v47, v92, v93
	v_max3_f32 v46, v46, v91, v74
	v_max3_f32 v47, v47, v76, v77
	v_max3_f32 v46, v46, v75, v94
	v_max3_f32 v47, v47, v96, v97
	v_max3_f32 v48, v46, v95, v78
	v_max3_f32 v47, v47, v80, v81
	v_max3_f32 v47, v48, v79, v47
	v_mov_b32_e32 v48, v47
	s_nop 1
	v_permlane32_swap_b32_e32 v47, v48
	v_max_f32_e32 v47, v47, v48
	v_cmp_lt_f32_e32 vcc, s51, v47
	s_cmp_lg_u64 vcc, 0
	v_add_f32_e32 v46, v200, v98
	s_cselect_b64 s[0:1], -1, 0
	s_cbranch_vccnz .LBB0_695

.LBB0_707:
	s_add_i32 s22, s23, 2
	v_add_u32_e32 v186, s0, v207
	ds_read_b64_tr_b16 v[178:179], v186 offset:24576
	ds_read_b64_tr_b16 v[180:181], v186 offset:25088
	s_waitcnt lgkmcnt(9)
	v_mfma_f32_32x32x16_bf16 v[98:113], v[174:177], v[142:145], v[34:49]
	v_add_f32_e32 v82, v66, v67
	v_add_f32_e32 v82, v68, v82
	v_add_f32_e32 v82, v69, v82
	v_add_f32_e32 v82, v70, v82
	v_add_f32_e32 v82, v71, v82
	v_cvt_pk_bf16_f32 v134, v66, v67
	v_cvt_pk_bf16_f32 v135, v68, v69
	ds_read_b64_tr_b16 v[174:175], v186 offset:28672
	ds_read_b64_tr_b16 v[176:177], v186 offset:29184
	v_add_f32_e32 v66, v72, v82
	s_waitcnt lgkmcnt(10)
	v_mfma_f32_32x32x16_bf16 v[82:97], v[170:173], v[142:145], v[34:49]
	v_add_f32_e32 v66, v73, v66
	v_add_f32_e32 v66, v74, v66
	v_add_f32_e32 v114, v75, v66
	v_cvt_pk_bf16_f32 v136, v70, v71
	v_cvt_pk_bf16_f32 v137, v72, v73
	ds_read_b64_tr_b16 v[66:67], v186 offset:25600
	ds_read_b64_tr_b16 v[68:69], v186 offset:26112
	s_waitcnt lgkmcnt(11)
	v_mfma_f32_32x32x16_bf16 v[98:113], v[166:169], v[138:141], v[98:113]
	v_add_f32_e32 v70, v76, v114
	v_add_f32_e32 v70, v77, v70
	v_add_f32_e32 v70, v78, v70
	v_add_f32_e32 v114, v79, v70
	v_cvt_pk_bf16_f32 v126, v74, v75
	v_cvt_pk_bf16_f32 v127, v76, v77
	ds_read_b64_tr_b16 v[70:71], v186 offset:29696
	ds_read_b64_tr_b16 v[72:73], v186 offset:30208
	s_waitcnt lgkmcnt(12)
	v_mfma_f32_32x32x16_bf16 v[82:97], v[162:165], v[138:141], v[82:97]
	v_add_f32_e32 v74, v80, v114
	v_add_f32_e32 v74, v81, v74
	v_add_f32_e32 v74, v50, v74
	v_add_f32_e32 v114, v51, v74
	v_cvt_pk_bf16_f32 v128, v78, v79
	v_cvt_pk_bf16_f32 v129, v80, v81
	ds_read_b64_tr_b16 v[74:75], v186 offset:26624
	ds_read_b64_tr_b16 v[76:77], v186 offset:27136
	s_waitcnt lgkmcnt(13)
	v_mfma_f32_32x32x16_bf16 v[98:113], v[158:161], v[130:133], v[98:113]
	v_add_f32_e32 v78, v52, v114
	v_add_f32_e32 v78, v53, v78
	v_add_f32_e32 v78, v54, v78
	v_add_f32_e32 v78, v55, v78
	v_cvt_pk_bf16_f32 v118, v50, v51
	v_cvt_pk_bf16_f32 v119, v52, v53
	ds_read_b64_tr_b16 v[50:51], v186 offset:30720
	ds_read_b64_tr_b16 v[52:53], v186 offset:31232
	s_waitcnt lgkmcnt(14)
	v_mfma_f32_32x32x16_bf16 v[82:97], v[154:157], v[130:133], v[82:97]
	v_add_f32_e32 v78, v56, v78
	v_add_f32_e32 v78, v57, v78
	v_add_f32_e32 v78, v58, v78
	v_add_f32_e32 v78, v59, v78
	v_cvt_pk_bf16_f32 v120, v54, v55
	v_cvt_pk_bf16_f32 v121, v56, v57
	ds_read_b64_tr_b16 v[54:55], v186 offset:27648
	ds_read_b64_tr_b16 v[56:57], v186 offset:28160
	s_waitcnt lgkmcnt(14)
	v_mfma_f32_32x32x16_bf16 v[98:113], v[150:153], v[122:125], v[98:113]
	v_add_f32_e32 v78, v60, v78
	v_add_f32_e32 v78, v61, v78
	v_add_f32_e32 v78, v62, v78
	v_add_f32_e32 v78, v63, v78
	v_cvt_pk_bf16_f32 v114, v58, v59
	v_cvt_pk_bf16_f32 v115, v60, v61
	ds_read_b64_tr_b16 v[58:59], v186 offset:31744
	ds_read_b64_tr_b16 v[60:61], v186 offset:32256
	v_mfma_f32_32x32x16_bf16 v[82:97], v[146:149], v[122:125], v[82:97]
	v_add_f32_e32 v78, v64, v78
	v_add_f32_e32 v78, v65, v78
	v_add_f32_e32 v78, 0, v78
	v_cvt_pk_bf16_f32 v116, v62, v63
	v_cvt_pk_bf16_f32 v117, v64, v65
	s_cmpk_gt_u32 s22, 0x7c
	s_cselect_b64 s[0:1], -1, 0
	s_cmpk_lt_u32 s22, 0x7d
	s_cselect_b32 s4, 0, 0xffffff80
	s_cselect_b32 s5, s9, s20
	s_add_i32 s4, s4, s23
	s_lshl_b32 s4, s4, 6
	s_add_i32 s4, s4, s5
	s_addk_i32 s4, 0x140
	v_mad_i64_i32 v[62:63], s[4:5], s4, v217, v[192:193]
	s_add_i32 s4, s24, s18
	s_mov_b32 s5, m0
	s_mov_b32 m0, s4
	s_nop 0
	global_load_lds_dwordx4 v[62:63], off
	s_mov_b32 m0, s5
	v_max_f32_e32 v62, v98, v99
	v_max3_f32 v63, v100, v101, v83
	v_max3_f32 v62, v62, v82, v84
	v_max3_f32 v62, v62, v85, v102
	v_max3_f32 v63, v63, v104, v105
	v_max3_f32 v62, v62, v103, v86
	v_max3_f32 v63, v63, v88, v89
	v_max3_f32 v62, v62, v87, v106
	v_max3_f32 v63, v63, v108, v109
	v_max3_f32 v62, v62, v107, v90
	v_max3_f32 v63, v63, v92, v93
	v_max3_f32 v62, v62, v91, v110
	v_max3_f32 v63, v63, v112, v113
	v_max3_f32 v62, v62, v111, v94
	v_max3_f32 v63, v63, v96, v97
	v_max3_f32 v62, v62, v95, v63
	v_mov_b32_e32 v63, v62
	s_nop 1
	v_permlane32_swap_b32_e32 v62, v63
	v_max_f32_e32 v62, v62, v63
	s_add_i32 s4, s21, s19
	s_mov_b32 s5, m0
	s_mov_b32 m0, s4
	s_nop 0
	global_load_lds_dwordx4 v[196:197], off
	s_mov_b32 m0, s5
	v_cmp_lt_f32_e32 vcc, s51, v62
	s_cmp_lg_u64 vcc, 0
	v_add_f32_e32 v224, v224, v78
	s_cselect_b64 s[4:5], -1, 0
	s_cbranch_vccnz .LBB0_715

.LBB0_710:
	s_add_i32 s4, s21, 0x2000
	s_cmpk_lg_i32 s21, 0x4000
	s_cselect_b32 s25, s4, 0
	v_add_u32_e32 v186, s24, v207
	ds_read_b64_tr_b16 v[150:151], v186 offset:24576
	ds_read_b64_tr_b16 v[152:153], v186 offset:25088
	s_waitcnt lgkmcnt(9)
	v_mfma_f32_32x32x16_bf16 v[66:81], v[62:65], v[142:145], v[34:49]
	v_add_f32_e32 v50, v98, v99
	v_add_f32_e32 v50, v100, v50
	v_add_f32_e32 v50, v101, v50
	v_add_f32_e32 v50, v102, v50
	v_add_f32_e32 v50, v103, v50
	v_cvt_pk_bf16_f32 v134, v98, v99
	v_cvt_pk_bf16_f32 v135, v100, v101
	ds_read_b64_tr_b16 v[146:147], v186 offset:28672
	ds_read_b64_tr_b16 v[148:149], v186 offset:29184
	v_add_f32_e32 v50, v104, v50
	v_add_f32_e32 v50, v105, v50
	v_add_f32_e32 v50, v106, v50
	v_add_f32_e32 v114, v107, v50
	s_waitcnt lgkmcnt(10)
	v_mfma_f32_32x32x16_bf16 v[50:65], v[174:177], v[142:145], v[34:49]
	v_cvt_pk_bf16_f32 v136, v102, v103
	v_cvt_pk_bf16_f32 v137, v104, v105
	ds_read_b64_tr_b16 v[98:99], v186 offset:25600
	ds_read_b64_tr_b16 v[100:101], v186 offset:26112
	s_waitcnt lgkmcnt(11)
	v_mfma_f32_32x32x16_bf16 v[66:81], v[178:181], v[138:141], v[66:81]
	v_add_f32_e32 v102, v108, v114
	v_add_f32_e32 v102, v109, v102
	v_add_f32_e32 v102, v110, v102
	v_add_f32_e32 v114, v111, v102
	v_cvt_pk_bf16_f32 v126, v106, v107
	v_cvt_pk_bf16_f32 v127, v108, v109
	ds_read_b64_tr_b16 v[102:103], v186 offset:29696
	ds_read_b64_tr_b16 v[104:105], v186 offset:30208
	s_waitcnt lgkmcnt(12)
	v_mfma_f32_32x32x16_bf16 v[50:65], v[170:173], v[138:141], v[50:65]
	v_add_f32_e32 v106, v112, v114
	v_add_f32_e32 v106, v113, v106
	v_add_f32_e32 v106, v82, v106
	v_add_f32_e32 v114, v83, v106
	v_cvt_pk_bf16_f32 v128, v110, v111
	v_cvt_pk_bf16_f32 v129, v112, v113
	ds_read_b64_tr_b16 v[106:107], v186 offset:26624
	ds_read_b64_tr_b16 v[108:109], v186 offset:27136
	s_waitcnt lgkmcnt(13)
	v_mfma_f32_32x32x16_bf16 v[66:81], v[166:169], v[130:133], v[66:81]
	v_add_f32_e32 v110, v84, v114
	v_add_f32_e32 v110, v85, v110
	v_add_f32_e32 v110, v86, v110
	v_add_f32_e32 v110, v87, v110
	v_cvt_pk_bf16_f32 v118, v82, v83
	v_cvt_pk_bf16_f32 v119, v84, v85
	ds_read_b64_tr_b16 v[82:83], v186 offset:30720
	ds_read_b64_tr_b16 v[84:85], v186 offset:31232
	s_waitcnt lgkmcnt(14)
	v_mfma_f32_32x32x16_bf16 v[50:65], v[162:165], v[130:133], v[50:65]
	v_add_f32_e32 v110, v88, v110
	v_add_f32_e32 v110, v89, v110
	v_add_f32_e32 v110, v90, v110
	v_add_f32_e32 v110, v91, v110
	v_cvt_pk_bf16_f32 v120, v86, v87
	v_cvt_pk_bf16_f32 v121, v88, v89
	ds_read_b64_tr_b16 v[86:87], v186 offset:27648
	ds_read_b64_tr_b16 v[88:89], v186 offset:28160
	s_waitcnt lgkmcnt(14)
	v_mfma_f32_32x32x16_bf16 v[66:81], v[158:161], v[122:125], v[66:81]
	v_add_f32_e32 v110, v92, v110
	v_add_f32_e32 v110, v93, v110
	v_add_f32_e32 v110, v94, v110
	v_add_f32_e32 v110, v95, v110
	v_cvt_pk_bf16_f32 v114, v90, v91
	v_cvt_pk_bf16_f32 v115, v92, v93
	ds_read_b64_tr_b16 v[90:91], v186 offset:31744
	ds_read_b64_tr_b16 v[92:93], v186 offset:32256
	v_mfma_f32_32x32x16_bf16 v[50:65], v[154:157], v[122:125], v[50:65]
	v_add_f32_e32 v110, v96, v110
	v_add_f32_e32 v110, v97, v110
	v_add_f32_e32 v110, 0, v110
	v_cvt_pk_bf16_f32 v116, v94, v95
	v_cvt_pk_bf16_f32 v117, v96, v97
	s_cmpk_lt_u32 s22, 0x7c
	s_cselect_b32 s4, 0, 0xffffff80
	s_cselect_b32 s5, s9, s20
	s_add_i32 s4, s4, s23
	s_lshl_b32 s4, s4, 6
	s_add_i32 s4, s4, s5
	s_addk_i32 s4, 0x180
	v_mad_i64_i32 v[94:95], s[4:5], s4, v217, v[192:193]
	s_add_i32 s4, s21, s18
	s_mov_b32 s5, m0
	s_mov_b32 m0, s4
	s_nop 0
	global_load_lds_dwordx4 v[94:95], off
	s_mov_b32 m0, s5
	v_lshl_add_u64 v[94:95], v[196:197], 0, s[30:31]
	s_add_i32 s4, s25, s19
	s_mov_b32 s5, m0
	s_mov_b32 m0, s4
	s_nop 0
	global_load_lds_dwordx4 v[94:95], off
	s_mov_b32 m0, s5
	v_max_f32_e32 v94, v66, v67
	v_max3_f32 v95, v68, v69, v51
	v_max3_f32 v94, v94, v50, v52
	v_max3_f32 v94, v94, v53, v70
	v_max3_f32 v95, v95, v72, v73
	v_max3_f32 v94, v94, v71, v54
	v_max3_f32 v95, v95, v56, v57
	v_max3_f32 v94, v94, v55, v74
	v_max3_f32 v95, v95, v76, v77
	v_max3_f32 v94, v94, v75, v58
	v_max3_f32 v95, v95, v60, v61
	v_max3_f32 v94, v94, v59, v78
	v_max3_f32 v95, v95, v80, v81
	v_max3_f32 v94, v94, v79, v62
	v_max3_f32 v95, v95, v64, v65
	v_max3_f32 v94, v94, v63, v95
	v_mov_b32_e32 v95, v94
	s_nop 1
	v_permlane32_swap_b32_e32 v94, v95
	v_max_f32_e32 v94, v94, v95
	v_cmp_lt_f32_e32 vcc, s51, v94
	s_cmp_lg_u64 vcc, 0
	v_add_f32_e32 v224, v224, v110
	s_cselect_b64 s[4:5], -1, 0
	s_cbranch_vccnz .LBB0_718

.LBB0_724:
	v_max_f32_e32 v62, v98, v99
	v_max3_f32 v63, v100, v101, v83
	v_max3_f32 v62, v62, v82, v84
	v_max3_f32 v62, v62, v85, v102
	v_max3_f32 v63, v63, v104, v105
	v_max3_f32 v62, v62, v103, v86
	v_max3_f32 v63, v63, v88, v89
	v_max3_f32 v62, v62, v87, v106
	v_max3_f32 v63, v63, v108, v109
	v_max3_f32 v62, v62, v107, v90
	v_max3_f32 v63, v63, v92, v93
	v_max3_f32 v62, v62, v91, v110
	v_max3_f32 v63, v63, v112, v113
	v_max3_f32 v62, v62, v111, v94
	v_max3_f32 v63, v63, v96, v97
	v_max3_f32 v62, v62, v95, v63
	v_mov_b32_e32 v63, v62
	s_nop 1
	v_permlane32_swap_b32_e32 v62, v63
	v_max_f32_e32 v62, v62, v63
	s_add_i32 s4, s22, s19
	s_mov_b32 s5, m0
	s_mov_b32 m0, s4
	s_nop 0
	global_load_lds_dwordx4 v[194:195], off
	s_mov_b32 m0, s5
	v_cmp_lt_f32_e32 vcc, s51, v62
	s_cmp_lg_u64 vcc, 0
	v_add_f32_e32 v196, v224, v78
	s_cselect_b64 s[4:5], -1, 0
	s_cbranch_vccnz .LBB0_750

.LBB0_735:
	s_add_i32 s6, s22, 0x2000
	s_cmpk_lg_i32 s22, 0x4000
	s_cselect_b32 s23, s6, 0
	v_lshl_add_u64 v[94:95], v[194:195], 0, s[30:31]
	s_add_i32 s6, s23, s19
	s_mov_b32 s7, m0
	s_mov_b32 m0, s6
	s_nop 0
	global_load_lds_dwordx4 v[94:95], off
	s_mov_b32 m0, s7
	v_max_f32_e32 v94, v66, v67
	v_max3_f32 v95, v68, v69, v51
	v_max3_f32 v94, v94, v50, v52
	v_max3_f32 v94, v94, v53, v70
	v_max3_f32 v95, v95, v72, v73
	v_max3_f32 v94, v94, v71, v54
	v_max3_f32 v95, v95, v56, v57
	v_max3_f32 v94, v94, v55, v74
	v_max3_f32 v95, v95, v76, v77
	v_max3_f32 v94, v94, v75, v58
	v_max3_f32 v95, v95, v60, v61
	v_max3_f32 v94, v94, v59, v78
	v_max3_f32 v95, v95, v80, v81
	v_max3_f32 v94, v94, v79, v62
	v_max3_f32 v95, v95, v64, v65
	v_max3_f32 v94, v94, v63, v95
	v_mov_b32_e32 v95, v94
	s_nop 1
	v_permlane32_swap_b32_e32 v94, v95
	v_max_f32_e32 v94, v94, v95
	v_cmp_lt_f32_e32 vcc, s51, v94
	s_cmp_lg_u64 vcc, 0
	v_add_f32_e32 v224, v196, v110
	s_cselect_b64 s[6:7], -1, 0
	s_cbranch_vccnz .LBB0_753

.LBB0_756:
	ds_read_b64_tr_b16 v[98:99], v207 offset:32768
	ds_read_b64_tr_b16 v[100:101], v207 offset:33280
	v_add_f32_e32 v82, v66, v67
	v_add_f32_e32 v82, v68, v82
	v_add_f32_e32 v82, v69, v82
	v_add_f32_e32 v82, v70, v82
	v_add_f32_e32 v102, v71, v82
	s_waitcnt lgkmcnt(9)
	v_mfma_f32_32x32x16_bf16 v[82:97], v[174:177], v[142:145], v[34:49]
	v_cvt_pk_bf16_f32 v134, v66, v67
	v_cvt_pk_bf16_f32 v135, v68, v69
	ds_read_b64_tr_b16 v[66:67], v207 offset:36864
	ds_read_b64_tr_b16 v[68:69], v207 offset:37376
	s_waitcnt lgkmcnt(10)
	v_mfma_f32_32x32x16_bf16 v[34:49], v[170:173], v[142:145], v[34:49]
	v_add_f32_e32 v102, v72, v102
	v_add_f32_e32 v102, v73, v102
	v_add_f32_e32 v102, v74, v102
	v_add_f32_e32 v102, v75, v102
	v_cvt_pk_bf16_f32 v136, v70, v71
	v_cvt_pk_bf16_f32 v137, v72, v73
	ds_read_b64_tr_b16 v[70:71], v207 offset:33792
	ds_read_b64_tr_b16 v[72:73], v207 offset:34304
	s_waitcnt lgkmcnt(11)
	v_mfma_f32_32x32x16_bf16 v[82:97], v[166:169], v[138:141], v[82:97]
	v_add_f32_e32 v102, v76, v102
	v_add_f32_e32 v102, v77, v102
	v_add_f32_e32 v102, v78, v102
	v_add_f32_e32 v102, v79, v102
	v_cvt_pk_bf16_f32 v126, v74, v75
	v_cvt_pk_bf16_f32 v127, v76, v77
	ds_read_b64_tr_b16 v[74:75], v207 offset:37888
	ds_read_b64_tr_b16 v[76:77], v207 offset:38400
	s_waitcnt lgkmcnt(12)
	v_mfma_f32_32x32x16_bf16 v[34:49], v[162:165], v[138:141], v[34:49]
	v_add_f32_e32 v102, v80, v102
	v_add_f32_e32 v102, v81, v102
	v_add_f32_e32 v102, v50, v102
	v_add_f32_e32 v102, v51, v102
	v_cvt_pk_bf16_f32 v128, v78, v79
	v_cvt_pk_bf16_f32 v129, v80, v81
	ds_read_b64_tr_b16 v[78:79], v207 offset:34816
	ds_read_b64_tr_b16 v[80:81], v207 offset:35328
	s_waitcnt lgkmcnt(13)
	v_mfma_f32_32x32x16_bf16 v[82:97], v[158:161], v[130:133], v[82:97]
	v_add_f32_e32 v102, v52, v102
	v_add_f32_e32 v102, v53, v102
	v_add_f32_e32 v102, v54, v102
	v_add_f32_e32 v106, v55, v102
	v_cvt_pk_bf16_f32 v118, v50, v51
	v_cvt_pk_bf16_f32 v119, v52, v53
	ds_read_b64_tr_b16 v[102:103], v207 offset:38912
	ds_read_b64_tr_b16 v[104:105], v207 offset:39424
	s_waitcnt lgkmcnt(14)
	v_mfma_f32_32x32x16_bf16 v[34:49], v[154:157], v[130:133], v[34:49]
	v_add_f32_e32 v50, v56, v106
	v_add_f32_e32 v50, v57, v50
	v_add_f32_e32 v50, v58, v50
	v_add_f32_e32 v50, v59, v50
	v_cvt_pk_bf16_f32 v120, v54, v55
	v_cvt_pk_bf16_f32 v121, v56, v57
	ds_read_b64_tr_b16 v[106:107], v207 offset:35840
	ds_read_b64_tr_b16 v[108:109], v207 offset:36352
	s_waitcnt lgkmcnt(14)
	v_mfma_f32_32x32x16_bf16 v[82:97], v[150:153], v[122:125], v[82:97]
	v_add_f32_e32 v50, v60, v50
	v_add_f32_e32 v50, v61, v50
	v_add_f32_e32 v50, v62, v50
	v_add_f32_e32 v50, v63, v50
	v_cvt_pk_bf16_f32 v114, v58, v59
	v_cvt_pk_bf16_f32 v115, v60, v61
	ds_read_b64_tr_b16 v[110:111], v207 offset:39936
	ds_read_b64_tr_b16 v[112:113], v207 offset:40448
	v_mfma_f32_32x32x16_bf16 v[34:49], v[146:149], v[122:125], v[34:49]
	v_add_f32_e32 v50, v64, v50
	v_add_f32_e32 v50, v65, v50
	v_add_f32_e32 v50, 0, v50
	v_cvt_pk_bf16_f32 v116, v62, v63
	v_cvt_pk_bf16_f32 v117, v64, v65
	v_max_f32_e32 v51, v82, v83
	s_nop 3
	v_max3_f32 v52, v84, v85, v35
	v_max3_f32 v51, v51, v34, v36
	v_max3_f32 v51, v51, v37, v86
	v_max3_f32 v52, v52, v88, v89
	v_max3_f32 v51, v51, v87, v38
	v_max3_f32 v52, v52, v40, v41
	v_max3_f32 v51, v51, v39, v90
	v_max3_f32 v52, v52, v92, v93
	v_max3_f32 v51, v51, v91, v42
	v_max3_f32 v52, v52, v44, v45
	v_max3_f32 v51, v51, v43, v94
	v_max3_f32 v52, v52, v96, v97
	v_max3_f32 v51, v51, v95, v46
	v_max3_f32 v52, v52, v48, v49
	v_add_f32_e32 v122, v224, v50
	v_max3_f32 v50, v51, v47, v52
	v_mov_b32_e32 v51, v50
	s_nop 1
	v_permlane32_swap_b32_e32 v50, v51
	v_max_f32_e32 v50, v50, v51
	v_cmp_lt_f32_e32 vcc, s51, v50
	s_cmp_lg_u64 vcc, 0
	s_cselect_b64 s[0:1], -1, 0
	s_cbranch_vccnz .LBB0_761

.LBB0_891:
	s_sext_i32_i8 s11, s3
	s_lshl_b32 s12, s11, 8
	s_add_i32 s18, s12, 0x4000
	s_add_i32 s3, s9, 0x280
	s_and_b64 s[0:1], exec, s[0:1]
	s_cselect_b32 s0, s9, s3
	s_mul_i32 s3, s18, 0xe00
	v_readlane_b32 s14, v254, 35
	s_mul_hi_u32 s1, s18, 0xe00
	v_readlane_b32 s15, v254, 36
	s_add_u32 s3, s14, s3
	s_addc_u32 s5, s15, s1
	s_ashr_i32 s1, s0, 31
	s_lshl_b64 s[0:1], s[0:1], 1
	s_add_u32 s10, s3, s0
	s_mov_b32 s3, s19
	s_addc_u32 s13, s5, s1
	s_lshl_b64 s[0:1], s[2:3], 1
	s_add_u32 s0, s14, s0
	s_mov_b32 s5, s19
	s_addc_u32 s1, s15, s1
	s_lshl_b64 s[2:3], s[4:5], 1
	s_add_u32 s14, s14, s2
	v_mov_b32_e32 v36, v191
	s_addc_u32 s15, s15, s3
	v_mov_b32_e32 v4, v1
	v_readfirstlane_b32 s3, v36
	v_and_b32_e32 v189, 63, v36
	s_ashr_i32 s7, s3, 6
	s_lshl_b32 s2, s7, 5
	s_mul_i32 s4, s7, 0x1c000
	v_mul_u32_u24_e32 v0, 0x700, v189
	s_mul_hi_i32 s5, s2, 0xe00
	s_add_u32 s16, s10, s4
	v_lshlrev_b32_e32 v0, 1, v0
	s_addc_u32 s17, s13, s5
	v_lshl_add_u64 v[2:3], s[0:1], 0, v[0:1]
	s_lshl_b32 s0, s7, 3
	s_ashr_i32 s1, s0, 31
	v_lshl_add_u64 v[34:35], s[0:1], 1, v[2:3]
	s_lshl_b32 s0, s7, 4
	v_bfe_u32 v0, v36, 2, 4
	v_and_or_b32 v0, s0, 48, v0
	v_mul_u32_u24_e32 v0, 0x700, v0
	s_ashr_i32 s0, s3, 3
	v_lshlrev_b32_e32 v0, 1, v0
	s_andn2_b32 s0, s0, 31
	v_lshl_add_u64 v[2:3], s[14:15], 0, v[0:1]
	s_ashr_i32 s1, s0, 31
	s_and_b32 s4, s3, 0x3fffffc0
	v_lshl_add_u64 v[2:3], s[0:1], 1, v[2:3]
	v_lshlrev_b32_e32 v194, 3, v36
	s_lshl_b32 s0, s7, 10
	v_and_b32_e32 v197, 24, v194
	s_cmp_lg_u32 0, -1
	v_lshlrev_b32_e32 v0, 1, v197
	s_cselect_b32 s1, 0, 0
	v_and_b32_e32 v195, 31, v36
	v_lshl_add_u64 v[38:39], v[2:3], 0, v[0:1]
	s_add_i32 s0, s1, s0
	v_mad_u64_u32 v[2:3], s[14:15], s18, v217, v[34:35]
	s_mov_b32 s1, m0
	s_mov_b32 m0, s0
	s_nop 0
	global_load_lds_dwordx4 v[2:3], off
	s_mov_b32 m0, s1
	s_add_i32 s3, s0, 0x6000
	v_mad_u64_u32 v[2:3], s[14:15], s18, v217, v[38:39]
	s_mov_b32 s1, m0
	s_mov_b32 m0, s3
	s_nop 0
	global_load_lds_dwordx4 v[2:3], off
	s_mov_b32 m0, s1
	v_mul_u32_u24_e32 v0, 0x700, v195
	v_bfe_u32 v196, v36, 5, 1
	s_add_i32 s1, s12, 0x4040
	v_lshlrev_b32_e32 v0, 1, v0
	v_mad_u64_u32 v[2:3], s[14:15], s1, v217, v[34:35]
	s_add_i32 s5, s0, 0x2000
	s_mov_b32 s10, m0
	s_mov_b32 m0, s5
	s_nop 0
	global_load_lds_dwordx4 v[2:3], off
	s_mov_b32 m0, s10
	v_lshl_or_b32 v0, v196, 4, v0
	global_load_dwordx4 v[142:145], v0, s[16:17]
	global_load_dwordx4 v[138:141], v0, s[16:17] offset:32
	global_load_dwordx4 v[130:133], v0, s[16:17] offset:64
	global_load_dwordx4 v[114:117], v0, s[16:17] offset:96
	v_lshlrev_b32_e32 v2, 4, v195
	v_lshl_add_u32 v0, v196, 10, 0
	v_add_u32_e32 v203, v0, v2
	v_mov_b32_e32 v2, v1
	v_mov_b32_e32 v3, v1
	v_mov_b32_e32 v5, v1
	v_mov_b32_e32 v6, v1
	v_mov_b32_e32 v7, v1
	v_mov_b32_e32 v8, v1
	v_mov_b32_e32 v9, v1
	v_mov_b32_e32 v10, v1
	v_mov_b32_e32 v11, v1
	v_mov_b32_e32 v12, v1
	v_mov_b32_e32 v13, v1
	v_mov_b32_e32 v14, v1
	v_mov_b32_e32 v15, v1
	v_mov_b32_e32 v0, v1
	v_mov_b64_e32 v[16:17], v[14:15]
	v_mov_b64_e32 v[14:15], v[12:13]
	v_mov_b64_e32 v[12:13], v[10:11]
	v_mov_b64_e32 v[10:11], v[8:9]
	v_mov_b64_e32 v[8:9], v[6:7]
	v_mov_b64_e32 v[6:7], v[4:5]
	v_mov_b64_e32 v[4:5], v[2:3]
	v_mov_b64_e32 v[2:3], v[0:1]
	s_add_i32 s5, s12, 0x4080
	v_mad_u64_u32 v[18:19], s[14:15], s5, v217, v[34:35]
	s_add_i32 s5, s0, 0x4000
	s_mov_b32 s10, m0
	s_mov_b32 m0, s5
	s_nop 0
	global_load_lds_dwordx4 v[18:19], off
	s_mov_b32 m0, s10
	s_waitcnt vmcnt(3) lgkmcnt(0)
	s_barrier
	ds_read_b128 v[40:43], v203
	ds_read_b128 v[44:47], v203 offset:512
	s_waitcnt vmcnt(3) lgkmcnt(1)
	v_mfma_f32_32x32x16_bf16 v[18:33], v[40:43], v[142:145], v[2:17]
	s_lshl_b32 s4, s4, 2
	s_addk_i32 s12, 0x40c0
	s_add_i32 s10, s4, 0
	v_lshlrev_b32_e32 v0, 1, v36
	v_lshlrev_b32_e32 v36, 4, v36
	v_and_b32_e32 v0, 32, v0
	v_and_b32_e32 v36, 0xc0, v36
	s_waitcnt lgkmcnt(0)
	v_mfma_f32_32x32x16_bf16 v[2:17], v[44:47], v[142:145], v[2:17]
	ds_read_b128 v[40:43], v203 offset:2048
	ds_read_b128 v[44:47], v203 offset:2560
	v_lshl_or_b32 v198, v196, 8, v36
	v_add3_u32 v36, 0, v0, v197
	v_add_u32_e32 v202, v36, v198
	v_cmp_gt_u32_e64 s[40:41], 32, v189
	v_lshl_add_u32 v199, v195, 2, s10
	s_waitcnt vmcnt(2) lgkmcnt(1)
	v_mfma_f32_32x32x16_bf16 v[18:33], v[40:43], v[138:141], v[18:33]
	s_waitcnt lgkmcnt(0)
	v_mfma_f32_32x32x16_bf16 v[2:17], v[44:47], v[138:141], v[2:17]
	ds_read_b128 v[40:43], v203 offset:4096
	ds_read_b128 v[44:47], v203 offset:4608
	s_waitcnt vmcnt(1) lgkmcnt(1)
	v_mfma_f32_32x32x16_bf16 v[18:33], v[40:43], v[130:133], v[18:33]
	s_waitcnt lgkmcnt(0)
	v_mfma_f32_32x32x16_bf16 v[2:17], v[44:47], v[130:133], v[2:17]
	ds_read_b128 v[40:43], v203 offset:6144
	ds_read_b128 v[44:47], v203 offset:6656
	s_waitcnt vmcnt(0) lgkmcnt(1)
	v_mfma_f32_32x32x16_bf16 v[18:33], v[40:43], v[114:117], v[18:33]
	s_waitcnt lgkmcnt(0)
	v_mfma_f32_32x32x16_bf16 v[2:17], v[44:47], v[114:117], v[2:17]
	s_nop 15
	s_nop 7
	s_nop 0
	v_max3_f32 v37, v18, v19, v2
	v_max3_f32 v40, v20, v21, v3
	s_nop 0
	v_max3_f32 v37, v37, v4, v5
	v_max3_f32 v40, v40, v24, v25
	s_nop 0
	v_max3_f32 v37, v37, v22, v23
	v_max3_f32 v40, v40, v8, v9
	s_nop 0
	v_max3_f32 v37, v37, v6, v7
	v_max3_f32 v40, v40, v28, v29
	s_nop 0
	v_max3_f32 v37, v37, v26, v27
	v_max3_f32 v40, v40, v12, v13
	s_nop 0
	v_max3_f32 v37, v37, v10, v11
	v_max3_f32 v40, v40, v32, v33
	s_nop 0
	v_max3_f32 v37, v37, v30, v31
	v_max3_f32 v40, v40, v16, v17
	s_nop 0
	v_max3_f32 v37, v37, v14, v15
	s_nop 0
	v_max_f32_e32 v37, v37, v40
	s_nop 0
	v_mov_b32_e32 v40, v37
	s_nop 1
	v_permlane32_swap_b32_e32 v37, v40
	v_max_f32_e32 v37, v37, v40
	s_nop 0
	v_add_f32_e32 v200, v1, v37
	v_sub_f32_e32 v40, v2, v37
	v_sub_f32_e32 v18, v18, v37
	v_sub_f32_e32 v19, v19, v37
	v_sub_f32_e32 v41, v3, v37
	v_sub_f32_e32 v20, v20, v37
	s_nop 0
	v_xor_b32_e32 v2, 0x80000000, v200
	v_sub_f32_e32 v42, v4, v37
	v_sub_f32_e32 v21, v21, v37
	v_sub_f32_e32 v43, v5, v37
	v_sub_f32_e32 v22, v22, v37
	v_sub_f32_e32 v44, v6, v37
	v_sub_f32_e32 v23, v23, v37
	v_sub_f32_e32 v45, v7, v37
	v_sub_f32_e32 v24, v24, v37
	v_sub_f32_e32 v46, v8, v37
	v_sub_f32_e32 v25, v25, v37
	v_sub_f32_e32 v47, v9, v37
	v_sub_f32_e32 v26, v26, v37
	v_sub_f32_e32 v48, v10, v37
	v_sub_f32_e32 v27, v27, v37
	v_sub_f32_e32 v49, v11, v37
	v_sub_f32_e32 v28, v28, v37
	v_sub_f32_e32 v50, v12, v37
	v_sub_f32_e32 v29, v29, v37
	v_sub_f32_e32 v51, v13, v37
	v_sub_f32_e32 v30, v30, v37
	v_sub_f32_e32 v52, v14, v37
	v_sub_f32_e32 v31, v31, v37
	v_sub_f32_e32 v53, v15, v37
	v_sub_f32_e32 v32, v32, v37
	v_sub_f32_e32 v54, v16, v37
	v_sub_f32_e32 v33, v33, v37
	v_sub_f32_e32 v37, v17, v37
	v_mov_b32_e32 v3, v2
	v_mov_b32_e32 v4, v2
	v_mov_b32_e32 v5, v2
	v_mov_b32_e32 v6, v2
	v_mov_b32_e32 v7, v2
	v_mov_b32_e32 v8, v2
	v_mov_b32_e32 v9, v2
	v_mov_b32_e32 v10, v2
	v_mov_b32_e32 v11, v2
	v_mov_b32_e32 v12, v2
	v_mov_b32_e32 v13, v2
	v_mov_b32_e32 v14, v2
	v_mov_b32_e32 v15, v2
	v_mov_b32_e32 v16, v2
	v_mov_b32_e32 v17, v2
	s_waitcnt vmcnt(0) lgkmcnt(0)
	s_barrier
	v_exp_f32_e32 v55, v18
	v_exp_f32_e32 v56, v19
	v_mad_u64_u32 v[18:19], s[4:5], s12, v217, v[34:35]
	s_mov_b32 s4, m0
	s_mov_b32 m0, s0
	s_nop 0
	global_load_lds_dwordx4 v[18:19], off
	s_mov_b32 m0, s4
	v_exp_f32_e32 v59, v22
	v_mad_u64_u32 v[18:19], s[4:5], s1, v217, v[38:39]
	s_add_i32 s1, s0, 0x8000
	s_mov_b32 s4, m0
	s_mov_b32 m0, s1
	s_nop 0
	global_load_lds_dwordx4 v[18:19], off
	s_mov_b32 m0, s4
	v_exp_f32_e32 v60, v23
	v_exp_f32_e32 v61, v24
	v_exp_f32_e32 v62, v25
	v_exp_f32_e32 v63, v26
	v_exp_f32_e32 v64, v27
	v_exp_f32_e32 v65, v28
	v_exp_f32_e32 v94, v29
	v_exp_f32_e32 v95, v30
	v_exp_f32_e32 v96, v31
	v_exp_f32_e32 v97, v32
	v_exp_f32_e32 v126, v33
	v_exp_f32_e32 v127, v40
	v_exp_f32_e32 v128, v41
	v_exp_f32_e32 v129, v42
	v_exp_f32_e32 v134, v43
	v_exp_f32_e32 v135, v44
	v_exp_f32_e32 v136, v45
	v_exp_f32_e32 v137, v46
	v_exp_f32_e32 v146, v47
	ds_read_b128 v[22:25], v203 offset:8192
	ds_read_b128 v[26:29], v203 offset:8704
	ds_read_b128 v[30:33], v203 offset:10240
	ds_read_b128 v[40:43], v203 offset:10752
	ds_read_b128 v[44:47], v203 offset:12288
	ds_read_b128 v[82:85], v203 offset:12800
	ds_read_b128 v[86:89], v203 offset:14336
	ds_read_b128 v[90:93], v203 offset:14848
	v_exp_f32_e32 v57, v20
	v_exp_f32_e32 v58, v21
	s_waitcnt vmcnt(2) lgkmcnt(0)
	s_barrier
	v_exp_f32_e32 v48, v48
	v_exp_f32_e32 v49, v49
	v_exp_f32_e32 v147, v50
	v_exp_f32_e32 v148, v51
	v_exp_f32_e32 v149, v52
	v_exp_f32_e32 v150, v53
	v_exp_f32_e32 v151, v54
	v_exp_f32_e32 v152, v37
	ds_read_b64_tr_b16 v[18:19], v202 offset:24576
	ds_read_b64_tr_b16 v[20:21], v202 offset:25088
	s_waitcnt lgkmcnt(9)
	v_mfma_f32_32x32x16_bf16 v[98:113], v[22:25], v[142:145], v[2:17]
	v_add_f32_e32 v34, v55, v56
	v_add_f32_e32 v34, v34, v57
	v_add_f32_e32 v34, v34, v58
	v_add_f32_e32 v34, v34, v59
	v_add_f32_e32 v50, v34, v60
	v_cvt_pk_bf16_f32 v122, v55, v56
	v_cvt_pk_bf16_f32 v123, v57, v58
	ds_read_b64_tr_b16 v[34:35], v202 offset:28672
	ds_read_b64_tr_b16 v[36:37], v202 offset:29184
	s_waitcnt lgkmcnt(10)
	v_mfma_f32_32x32x16_bf16 v[66:81], v[26:29], v[142:145], v[2:17]
	v_add_f32_e32 v22, v61, v50
	v_add_f32_e32 v22, v62, v22
	v_add_f32_e32 v22, v63, v22
	v_add_f32_e32 v22, v64, v22
	v_cvt_pk_bf16_f32 v124, v59, v60
	v_cvt_pk_bf16_f32 v125, v61, v62
	ds_read_b64_tr_b16 v[50:51], v202 offset:25600
	ds_read_b64_tr_b16 v[52:53], v202 offset:26112
	s_waitcnt lgkmcnt(11)
	v_mfma_f32_32x32x16_bf16 v[98:113], v[30:33], v[138:141], v[98:113]
	v_add_f32_e32 v22, v65, v22
	v_add_f32_e32 v22, v94, v22
	v_add_f32_e32 v22, v95, v22
	v_add_f32_e32 v22, v96, v22
	v_cvt_pk_bf16_f32 v118, v63, v64
	v_cvt_pk_bf16_f32 v119, v65, v94
	ds_read_b64_tr_b16 v[54:55], v202 offset:29696
	ds_read_b64_tr_b16 v[56:57], v202 offset:30208
	s_waitcnt lgkmcnt(12)
	v_mfma_f32_32x32x16_bf16 v[66:81], v[40:43], v[138:141], v[66:81]
	v_add_f32_e32 v22, v97, v22
	v_add_f32_e32 v22, v126, v22
	v_add_f32_e32 v22, v127, v22
	v_add_f32_e32 v22, v128, v22
	v_cvt_pk_bf16_f32 v120, v95, v96
	v_cvt_pk_bf16_f32 v121, v97, v126
	ds_read_b64_tr_b16 v[58:59], v202 offset:26624
	ds_read_b64_tr_b16 v[60:61], v202 offset:27136
	s_waitcnt lgkmcnt(13)
	v_mfma_f32_32x32x16_bf16 v[98:113], v[44:47], v[130:133], v[98:113]
	v_add_f32_e32 v22, v129, v22
	v_add_f32_e32 v22, v134, v22
	v_add_f32_e32 v22, v135, v22
	v_add_f32_e32 v22, v136, v22
	v_cvt_pk_bf16_f32 v126, v127, v128
	v_cvt_pk_bf16_f32 v127, v129, v134
	ds_read_b64_tr_b16 v[62:63], v202 offset:30720
	ds_read_b64_tr_b16 v[64:65], v202 offset:31232
	s_waitcnt lgkmcnt(14)
	v_mfma_f32_32x32x16_bf16 v[66:81], v[82:85], v[130:133], v[66:81]
	v_add_f32_e32 v22, v137, v22
	v_add_f32_e32 v22, v146, v22
	v_add_f32_e32 v22, v48, v22
	v_add_f32_e32 v22, v49, v22
	v_cvt_pk_bf16_f32 v128, v135, v136
	v_cvt_pk_bf16_f32 v129, v137, v146
	ds_read_b64_tr_b16 v[82:83], v202 offset:27648
	ds_read_b64_tr_b16 v[84:85], v202 offset:28160
	s_waitcnt lgkmcnt(14)
	v_mfma_f32_32x32x16_bf16 v[98:113], v[86:89], v[114:117], v[98:113]
	v_add_f32_e32 v22, v147, v22
	v_add_f32_e32 v22, v148, v22
	v_add_f32_e32 v22, v149, v22
	v_add_f32_e32 v22, v150, v22
	v_cvt_pk_bf16_f32 v134, v48, v49
	v_cvt_pk_bf16_f32 v135, v147, v148
	ds_read_b64_tr_b16 v[86:87], v202 offset:31744
	ds_read_b64_tr_b16 v[88:89], v202 offset:32256
	v_mfma_f32_32x32x16_bf16 v[66:81], v[90:93], v[114:117], v[66:81]
	v_add_f32_e32 v22, v151, v22
	v_add_f32_e32 v22, v152, v22
	v_add_f32_e32 v22, 0, v22
	v_cvt_pk_bf16_f32 v136, v149, v150
	v_cvt_pk_bf16_f32 v137, v151, v152
	s_mul_i32 s4, s11, 0xe0000
	s_ashr_i32 s5, s4, 31
	v_lshl_add_u64 v[192:193], v[38:39], 0, s[4:5]
	s_mov_b64 s[4:5], 0x3870000
	v_add_f32_e32 v204, 0, v22
	v_lshl_add_u64 v[22:23], v[192:193], 0, s[4:5]
	s_add_i32 s0, s0, 0xa000
	s_mov_b32 s1, m0
	s_mov_b32 m0, s0
	s_nop 0
	global_load_lds_dwordx4 v[22:23], off
	s_mov_b32 m0, s1
	v_max_f32_e32 v22, v98, v99
	v_max3_f32 v23, v100, v101, v67
	v_max3_f32 v22, v22, v66, v68
	v_max3_f32 v22, v22, v69, v102
	v_max3_f32 v23, v23, v104, v105
	v_max3_f32 v22, v22, v103, v70
	v_max3_f32 v23, v23, v72, v73
	v_max3_f32 v22, v22, v71, v106
	v_max3_f32 v23, v23, v108, v109
	v_max3_f32 v22, v22, v107, v74
	v_max3_f32 v23, v23, v76, v77
	v_max3_f32 v22, v22, v75, v110
	v_max3_f32 v23, v23, v112, v113
	v_max3_f32 v22, v22, v111, v78
	v_max3_f32 v23, v23, v80, v81
	v_max3_f32 v22, v22, v79, v23
	v_mov_b32_e32 v23, v22
	s_nop 1
	v_permlane32_swap_b32_e32 v22, v23
	v_max_f32_e32 v22, v22, v23
	v_cmp_lt_f32_e32 vcc, s51, v22
	s_cmp_lg_u64 vcc, 0
	s_cselect_b64 s[0:1], -1, 0
	s_cbranch_vccnz .LBB0_902

.LBB0_894:
	ds_read_b64_tr_b16 v[150:151], v202 offset:32768
	ds_read_b64_tr_b16 v[152:153], v202 offset:33280
	s_waitcnt lgkmcnt(9)
	v_mfma_f32_32x32x16_bf16 v[82:97], v[146:149], v[142:145], v[2:17]
	v_add_f32_e32 v50, v98, v99
	v_add_f32_e32 v50, v100, v50
	v_add_f32_e32 v50, v101, v50
	v_add_f32_e32 v50, v102, v50
	v_add_f32_e32 v50, v103, v50
	v_cvt_pk_bf16_f32 v122, v98, v99
	v_cvt_pk_bf16_f32 v123, v100, v101
	ds_read_b64_tr_b16 v[146:147], v202 offset:36864
	ds_read_b64_tr_b16 v[148:149], v202 offset:37376
	v_add_f32_e32 v50, v104, v50
	v_add_f32_e32 v50, v105, v50
	v_add_f32_e32 v50, v106, v50
	v_add_f32_e32 v118, v107, v50
	s_waitcnt lgkmcnt(10)
	v_mfma_f32_32x32x16_bf16 v[50:65], v[174:177], v[142:145], v[2:17]
	v_cvt_pk_bf16_f32 v124, v102, v103
	v_cvt_pk_bf16_f32 v125, v104, v105
	ds_read_b64_tr_b16 v[98:99], v202 offset:33792
	ds_read_b64_tr_b16 v[100:101], v202 offset:34304
	s_waitcnt lgkmcnt(11)
	v_mfma_f32_32x32x16_bf16 v[82:97], v[178:181], v[138:141], v[82:97]
	v_add_f32_e32 v102, v108, v118
	v_add_f32_e32 v102, v109, v102
	v_add_f32_e32 v102, v110, v102
	v_add_f32_e32 v126, v111, v102
	v_cvt_pk_bf16_f32 v118, v106, v107
	v_cvt_pk_bf16_f32 v119, v108, v109
	ds_read_b64_tr_b16 v[102:103], v202 offset:37888
	ds_read_b64_tr_b16 v[104:105], v202 offset:38400
	s_waitcnt lgkmcnt(12)
	v_mfma_f32_32x32x16_bf16 v[50:65], v[170:173], v[138:141], v[50:65]
	v_add_f32_e32 v106, v112, v126
	v_add_f32_e32 v106, v113, v106
	v_add_f32_e32 v106, v66, v106
	v_add_f32_e32 v126, v67, v106
	v_cvt_pk_bf16_f32 v120, v110, v111
	v_cvt_pk_bf16_f32 v121, v112, v113
	ds_read_b64_tr_b16 v[106:107], v202 offset:34816
	ds_read_b64_tr_b16 v[108:109], v202 offset:35328
	s_waitcnt lgkmcnt(13)
	v_mfma_f32_32x32x16_bf16 v[82:97], v[166:169], v[130:133], v[82:97]
	v_add_f32_e32 v110, v68, v126
	v_add_f32_e32 v110, v69, v110
	v_add_f32_e32 v110, v70, v110
	v_add_f32_e32 v110, v71, v110
	v_cvt_pk_bf16_f32 v126, v66, v67
	v_cvt_pk_bf16_f32 v127, v68, v69
	ds_read_b64_tr_b16 v[66:67], v202 offset:38912
	ds_read_b64_tr_b16 v[68:69], v202 offset:39424
	s_waitcnt lgkmcnt(14)
	v_mfma_f32_32x32x16_bf16 v[50:65], v[162:165], v[130:133], v[50:65]
	v_add_f32_e32 v110, v72, v110
	v_add_f32_e32 v110, v73, v110
	v_add_f32_e32 v110, v74, v110
	v_add_f32_e32 v110, v75, v110
	v_cvt_pk_bf16_f32 v128, v70, v71
	v_cvt_pk_bf16_f32 v129, v72, v73
	ds_read_b64_tr_b16 v[70:71], v202 offset:35840
	ds_read_b64_tr_b16 v[72:73], v202 offset:36352
	s_waitcnt lgkmcnt(14)
	v_mfma_f32_32x32x16_bf16 v[82:97], v[158:161], v[114:117], v[82:97]
	v_add_f32_e32 v110, v76, v110
	v_add_f32_e32 v110, v77, v110
	v_add_f32_e32 v110, v78, v110
	v_add_f32_e32 v110, v79, v110
	v_cvt_pk_bf16_f32 v134, v74, v75
	v_cvt_pk_bf16_f32 v135, v76, v77
	ds_read_b64_tr_b16 v[74:75], v202 offset:39936
	ds_read_b64_tr_b16 v[76:77], v202 offset:40448
	v_mfma_f32_32x32x16_bf16 v[50:65], v[154:157], v[114:117], v[50:65]
	v_add_f32_e32 v110, v80, v110
	v_add_f32_e32 v110, v81, v110
	v_add_f32_e32 v110, 0, v110
	v_cvt_pk_bf16_f32 v136, v78, v79
	v_cvt_pk_bf16_f32 v137, v80, v81
	s_mov_b64 s[0:1], 0x38a8000
	v_lshl_add_u64 v[78:79], v[192:193], 0, s[0:1]
	s_mov_b32 s0, m0
	s_mov_b32 m0, s3
	s_nop 0
	global_load_lds_dwordx4 v[78:79], off
	s_mov_b32 m0, s0
	v_max_f32_e32 v78, v82, v83
	s_nop 1
	v_max3_f32 v79, v84, v85, v51
	v_max3_f32 v78, v78, v50, v52
	v_max3_f32 v78, v78, v53, v86
	v_max3_f32 v79, v79, v88, v89
	v_max3_f32 v78, v78, v87, v54
	v_max3_f32 v79, v79, v56, v57
	v_max3_f32 v78, v78, v55, v90
	v_max3_f32 v79, v79, v92, v93
	v_max3_f32 v78, v78, v91, v58
	v_max3_f32 v79, v79, v60, v61
	v_max3_f32 v78, v78, v59, v94
	v_max3_f32 v79, v79, v96, v97
	v_max3_f32 v78, v78, v95, v62
	v_max3_f32 v79, v79, v64, v65
	v_max3_f32 v78, v78, v63, v79
	v_mov_b32_e32 v79, v78
	s_nop 1
	v_permlane32_swap_b32_e32 v78, v79
	v_max_f32_e32 v78, v78, v79
	v_cmp_lt_f32_e32 vcc, s51, v78
	s_cmp_lg_u64 vcc, 0
	v_add_f32_e32 v170, v204, v110
	s_cselect_b64 s[0:1], -1, 0
	s_cbranch_vccnz .LBB0_905

.LBB0_897:
	ds_read_b64_tr_b16 v[98:99], v202 offset:40960
	ds_read_b64_tr_b16 v[100:101], v202 offset:41472
	v_add_f32_e32 v66, v82, v83
	v_add_f32_e32 v66, v84, v66
	v_add_f32_e32 v66, v85, v66
	v_add_f32_e32 v66, v86, v66
	v_add_f32_e32 v106, v87, v66
	s_waitcnt lgkmcnt(9)
	v_mfma_f32_32x32x16_bf16 v[66:81], v[166:169], v[142:145], v[2:17]
	v_cvt_pk_bf16_f32 v122, v82, v83
	v_cvt_pk_bf16_f32 v123, v84, v85
	ds_read_b64_tr_b16 v[82:83], v202 offset:45056
	ds_read_b64_tr_b16 v[84:85], v202 offset:45568
	s_waitcnt lgkmcnt(10)
	v_mfma_f32_32x32x16_bf16 v[2:17], v[162:165], v[142:145], v[2:17]
	v_add_f32_e32 v106, v88, v106
	v_add_f32_e32 v106, v89, v106
	v_add_f32_e32 v106, v90, v106
	v_add_f32_e32 v106, v91, v106
	v_cvt_pk_bf16_f32 v124, v86, v87
	v_cvt_pk_bf16_f32 v125, v88, v89
	ds_read_b64_tr_b16 v[86:87], v202 offset:41984
	ds_read_b64_tr_b16 v[88:89], v202 offset:42496
	s_waitcnt lgkmcnt(11)
	v_mfma_f32_32x32x16_bf16 v[66:81], v[158:161], v[138:141], v[66:81]
	v_add_f32_e32 v106, v92, v106
	v_add_f32_e32 v106, v93, v106
	v_add_f32_e32 v106, v94, v106
	v_add_f32_e32 v106, v95, v106
	v_cvt_pk_bf16_f32 v118, v90, v91
	v_cvt_pk_bf16_f32 v119, v92, v93
	ds_read_b64_tr_b16 v[90:91], v202 offset:46080
	ds_read_b64_tr_b16 v[92:93], v202 offset:46592
	s_waitcnt lgkmcnt(12)
	v_mfma_f32_32x32x16_bf16 v[2:17], v[154:157], v[138:141], v[2:17]
	v_add_f32_e32 v106, v96, v106
	v_add_f32_e32 v106, v97, v106
	v_add_f32_e32 v106, v50, v106
	v_add_f32_e32 v106, v51, v106
	v_cvt_pk_bf16_f32 v120, v94, v95
	v_cvt_pk_bf16_f32 v121, v96, v97
	ds_read_b64_tr_b16 v[94:95], v202 offset:43008
	ds_read_b64_tr_b16 v[96:97], v202 offset:43520
	s_waitcnt lgkmcnt(13)
	v_mfma_f32_32x32x16_bf16 v[66:81], v[102:105], v[130:133], v[66:81]
	v_add_f32_e32 v102, v52, v106
	v_add_f32_e32 v102, v53, v102
	v_add_f32_e32 v102, v54, v102
	v_add_f32_e32 v106, v55, v102
	v_cvt_pk_bf16_f32 v126, v50, v51
	v_cvt_pk_bf16_f32 v127, v52, v53
	ds_read_b64_tr_b16 v[102:103], v202 offset:47104
	ds_read_b64_tr_b16 v[104:105], v202 offset:47616
	s_waitcnt lgkmcnt(14)
	v_mfma_f32_32x32x16_bf16 v[2:17], v[150:153], v[130:133], v[2:17]
	v_add_f32_e32 v50, v56, v106
	v_add_f32_e32 v50, v57, v50
	v_add_f32_e32 v50, v58, v50
	v_add_f32_e32 v50, v59, v50
	v_cvt_pk_bf16_f32 v128, v54, v55
	v_cvt_pk_bf16_f32 v129, v56, v57
	ds_read_b64_tr_b16 v[106:107], v202 offset:44032
	ds_read_b64_tr_b16 v[108:109], v202 offset:44544
	s_waitcnt lgkmcnt(14)
	v_mfma_f32_32x32x16_bf16 v[66:81], v[146:149], v[114:117], v[66:81]
	v_add_f32_e32 v50, v60, v50
	v_add_f32_e32 v50, v61, v50
	v_add_f32_e32 v50, v62, v50
	v_add_f32_e32 v50, v63, v50
	v_cvt_pk_bf16_f32 v134, v58, v59
	v_cvt_pk_bf16_f32 v135, v60, v61
	ds_read_b64_tr_b16 v[130:131], v202 offset:48128
	ds_read_b64_tr_b16 v[132:133], v202 offset:48640
	v_mfma_f32_32x32x16_bf16 v[2:17], v[110:113], v[114:117], v[2:17]
	v_add_f32_e32 v50, v64, v50
	v_add_f32_e32 v50, v65, v50
	v_add_f32_e32 v50, 0, v50
	v_cvt_pk_bf16_f32 v136, v62, v63
	v_cvt_pk_bf16_f32 v137, v64, v65
	v_max_f32_e32 v51, v66, v67
	s_nop 3
	v_max3_f32 v52, v68, v69, v3
	v_max3_f32 v51, v51, v2, v4
	v_max3_f32 v51, v51, v5, v70
	v_max3_f32 v52, v52, v72, v73
	v_max3_f32 v51, v51, v71, v6
	v_max3_f32 v52, v52, v8, v9
	v_max3_f32 v51, v51, v7, v74
	v_max3_f32 v52, v52, v76, v77
	v_max3_f32 v51, v51, v75, v10
	v_max3_f32 v52, v52, v12, v13
	v_max3_f32 v51, v51, v11, v78
	v_max3_f32 v52, v52, v80, v81
	v_max3_f32 v51, v51, v79, v14
	v_max3_f32 v52, v52, v16, v17
	v_add_f32_e32 v110, v170, v50
	v_max3_f32 v50, v51, v15, v52
	v_mov_b32_e32 v51, v50
	s_nop 1
	v_permlane32_swap_b32_e32 v50, v51
	v_max_f32_e32 v50, v50, v51
	v_cmp_lt_f32_e32 vcc, s51, v50
	s_cmp_lg_u64 vcc, 0
	s_cselect_b64 s[0:1], -1, 0
	s_cbranch_vccnz .LBB0_908
